# Down-GEMM residual epilogue: x loads software-pipelined 8 deep instead of load-wait-store x32
# speedup vs baseline: 1.0017x; 1.0017x over previous
.LBB0_363:
	s_lshl_b32 s31, s11, 8
	s_min_i32 s20, s11, 0x100
	s_ashr_i32 s62, s20, 5
	s_add_i32 s63, s31, 0xffff0000
	s_cmpk_gt_i32 s11, 0xff
	s_cselect_b32 s11, s63, s31
	v_add_u32_e32 v146, s11, v1
	s_mul_i32 s62, s62, 0x9000
	s_cselect_b32 s23, s69, s65
	s_cselect_b32 s22, s70, s68
	s_cselect_b32 s21, s37, s49
	s_cselect_b32 s20, s33, s48
	v_lshl_or_b32 v147, s92, 8, v149
	v_lshlrev_b32_e32 v147, 2, v147
	v_lshl_add_u32 v146, v146, 12, v147
	v_add_u32_e32 v147, s62, v147
	v_add_co_u32_e32 v160, vcc, s75, v147
	v_mov_b32_e32 v161, s76
	s_nop 1
	v_addc_co_u32_e32 v161, vcc, 0, v161, vcc
	global_load_dwordx4 v[138:141], v[160:161], off
	global_load_dwordx4 v[142:145], v146, s[22:23]
	s_add_u32 s62, s22, 0x10000
	s_addc_u32 s63, s23, 0
	global_load_dwordx4 v[152:155], v146, s[62:63]
	s_add_u32 s62, s22, 0x20000
	s_addc_u32 s63, s23, 0
	global_load_dwordx4 v[156:159], v146, s[62:63]
	s_waitcnt vmcnt(3)
	v_pk_mul_f32 v[138:139], v[138:139], 0.5 op_sel_hi:[1,0]
	v_pk_mul_f32 v[140:141], v[140:141], 0.5 op_sel_hi:[1,0]
	s_waitcnt vmcnt(2)
	v_pk_fma_f32 v[142:143], v[126:127], v[138:139], v[142:143]
	v_pk_fma_f32 v[144:145], v[128:129], v[140:141], v[144:145]
	global_store_dwordx4 v146, v[142:145], s[20:21]
	s_add_u32 s62, s22, 0x30000
	s_addc_u32 s63, s23, 0
	global_load_dwordx4 v[126:129], v146, s[62:63]
	s_waitcnt vmcnt(3)
	v_pk_fma_f32 v[152:153], v[122:123], v[138:139], v[152:153]
	v_pk_fma_f32 v[154:155], v[124:125], v[140:141], v[154:155]
	s_add_u32 vcc_lo, s20, 0x10000
	s_addc_u32 vcc_hi, s21, 0
	global_store_dwordx4 v146, v[152:155], vcc
	s_add_u32 s62, s22, 0x80000
	s_addc_u32 s63, s23, 0
	global_load_dwordx4 v[142:145], v146, s[62:63]
	s_add_u32 s62, s22, 0x90000
	s_addc_u32 s63, s23, 0
	global_load_dwordx4 v[122:125], v146, s[62:63]
	s_waitcnt vmcnt(5)
	v_pk_fma_f32 v[156:157], v[118:119], v[138:139], v[156:157]
	v_pk_fma_f32 v[158:159], v[120:121], v[140:141], v[158:159]
	s_add_u32 vcc_lo, s20, 0x20000
	s_addc_u32 vcc_hi, s21, 0
	global_store_dwordx4 v146, v[156:159], vcc
	s_add_u32 s62, s22, 0xa0000
	s_addc_u32 s63, s23, 0
	global_load_dwordx4 v[152:155], v146, s[62:63]
	s_add_u32 s62, s22, 0xb0000
	s_addc_u32 s63, s23, 0
	global_load_dwordx4 v[118:121], v146, s[62:63]
	s_waitcnt vmcnt(6)
	v_pk_fma_f32 v[126:127], v[114:115], v[138:139], v[126:127]
	v_pk_fma_f32 v[128:129], v[116:117], v[140:141], v[128:129]
	s_add_u32 vcc_lo, s20, 0x30000
	s_addc_u32 vcc_hi, s21, 0
	global_store_dwordx4 v146, v[126:129], vcc
	global_load_dwordx4 v[156:159], v[160:161], off offset:64
	global_load_dwordx4 v[114:117], v146, s[22:23] offset:64
	s_add_u32 s62, s22, 0x10000
	s_addc_u32 s63, s23, 0
	global_load_dwordx4 v[126:129], v146, s[62:63] offset:64
	s_waitcnt vmcnt(8)
	v_pk_fma_f32 v[142:143], v[110:111], v[138:139], v[142:143]
	v_pk_fma_f32 v[144:145], v[112:113], v[140:141], v[144:145]
	s_add_u32 vcc_lo, s20, 0x80000
	s_addc_u32 vcc_hi, s21, 0
	global_store_dwordx4 v146, v[142:145], vcc
	s_add_u32 s62, s22, 0x20000
	s_addc_u32 s63, s23, 0
	global_load_dwordx4 v[110:113], v146, s[62:63] offset:64
	s_add_u32 s62, s22, 0x30000
	s_addc_u32 s63, s23, 0
	global_load_dwordx4 v[142:145], v146, s[62:63] offset:64
	s_waitcnt vmcnt(10)
	v_pk_fma_f32 v[122:123], v[106:107], v[138:139], v[122:123]
	v_pk_fma_f32 v[124:125], v[108:109], v[140:141], v[124:125]
	s_add_u32 vcc_lo, s20, 0x90000
	s_addc_u32 vcc_hi, s21, 0
	global_store_dwordx4 v146, v[122:125], vcc
	s_add_u32 s62, s22, 0x80000
	s_addc_u32 s63, s23, 0
	global_load_dwordx4 v[106:109], v146, s[62:63] offset:64
	s_add_u32 s62, s22, 0x90000
	s_addc_u32 s63, s23, 0
	global_load_dwordx4 v[122:125], v146, s[62:63] offset:64
	s_waitcnt vmcnt(11)
	v_pk_fma_f32 v[152:153], v[102:103], v[138:139], v[152:153]
	v_pk_fma_f32 v[154:155], v[104:105], v[140:141], v[154:155]
	s_add_u32 vcc_lo, s20, 0xa0000
	s_addc_u32 vcc_hi, s21, 0
	global_store_dwordx4 v146, v[152:155], vcc
	s_add_u32 s62, s22, 0xa0000
	s_addc_u32 s63, s23, 0
	global_load_dwordx4 v[102:105], v146, s[62:63] offset:64
	s_waitcnt vmcnt(12)
	v_pk_fma_f32 v[118:119], v[98:99], v[138:139], v[118:119]
	v_pk_fma_f32 v[120:121], v[100:101], v[140:141], v[120:121]
	s_add_u32 vcc_lo, s20, 0xb0000
	s_addc_u32 vcc_hi, s21, 0
	global_store_dwordx4 v146, v[118:121], vcc
	s_add_u32 s62, s22, 0xb0000
	s_addc_u32 s63, s23, 0
	global_load_dwordx4 v[152:155], v146, s[62:63] offset:64
	s_waitcnt vmcnt(12)
	v_pk_mul_f32 v[156:157], v[156:157], 0.5 op_sel_hi:[1,0]
	v_pk_mul_f32 v[158:159], v[158:159], 0.5 op_sel_hi:[1,0]
	s_waitcnt vmcnt(11)
	v_pk_fma_f32 v[114:115], v[94:95], v[156:157], v[114:115]
	v_pk_fma_f32 v[116:117], v[96:97], v[158:159], v[116:117]
	global_store_dwordx4 v146, v[114:117], s[20:21] offset:64
	global_load_dwordx4 v[98:101], v146, s[22:23] offset:512
	s_waitcnt vmcnt(12)
	v_pk_fma_f32 v[126:127], v[90:91], v[156:157], v[126:127]
	v_pk_fma_f32 v[128:129], v[92:93], v[158:159], v[128:129]
	s_add_u32 vcc_lo, s20, 0x10000
	s_addc_u32 vcc_hi, s21, 0
	global_store_dwordx4 v146, v[126:129], vcc offset:64
	s_add_u32 s62, s22, 0x10000
	s_addc_u32 s63, s23, 0
	global_load_dwordx4 v[118:121], v146, s[62:63] offset:512
	s_waitcnt vmcnt(12)
	v_pk_fma_f32 v[110:111], v[86:87], v[156:157], v[110:111]
	v_pk_fma_f32 v[112:113], v[88:89], v[158:159], v[112:113]
	s_add_u32 vcc_lo, s20, 0x20000
	s_addc_u32 vcc_hi, s21, 0
	global_store_dwordx4 v146, v[110:113], vcc offset:64
	s_add_u32 s62, s22, 0x20000
	s_addc_u32 s63, s23, 0
	global_load_dwordx4 v[138:141], v146, s[62:63] offset:512
	s_waitcnt vmcnt(13)
	v_pk_fma_f32 v[142:143], v[82:83], v[156:157], v[142:143]
	v_pk_fma_f32 v[144:145], v[84:85], v[158:159], v[144:145]
	s_add_u32 vcc_lo, s20, 0x30000
	s_addc_u32 vcc_hi, s21, 0
	global_store_dwordx4 v146, v[142:145], vcc offset:64
	global_load_dwordx4 v[94:97], v[160:161], off offset:512
	s_add_u32 s62, s22, 0x30000
	s_addc_u32 s63, s23, 0
	global_load_dwordx4 v[114:117], v146, s[62:63] offset:512
	s_waitcnt vmcnt(14)
	v_pk_fma_f32 v[106:107], v[78:79], v[156:157], v[106:107]
	v_pk_fma_f32 v[108:109], v[80:81], v[158:159], v[108:109]
	s_add_u32 vcc_lo, s20, 0x80000
	s_addc_u32 vcc_hi, s21, 0
	global_store_dwordx4 v146, v[106:109], vcc offset:64
	s_add_u32 s62, s22, 0x80000
	s_addc_u32 s63, s23, 0
	global_load_dwordx4 v[90:93], v146, s[62:63] offset:512
	s_waitcnt vmcnt(15)
	v_pk_fma_f32 v[122:123], v[74:75], v[156:157], v[122:123]
	v_pk_fma_f32 v[124:125], v[76:77], v[158:159], v[124:125]
	s_add_u32 vcc_lo, s20, 0x90000
	s_addc_u32 vcc_hi, s21, 0
	global_store_dwordx4 v146, v[122:125], vcc offset:64
	s_add_u32 s62, s22, 0x90000
	s_addc_u32 s63, s23, 0
	global_load_dwordx4 v[126:129], v146, s[62:63] offset:512
	s_waitcnt vmcnt(15)
	v_pk_fma_f32 v[102:103], v[70:71], v[156:157], v[102:103]
	v_pk_fma_f32 v[104:105], v[72:73], v[158:159], v[104:105]
	s_add_u32 vcc_lo, s20, 0xa0000
	s_addc_u32 vcc_hi, s21, 0
	global_store_dwordx4 v146, v[102:105], vcc offset:64
	s_add_u32 s62, s22, 0xa0000
	s_addc_u32 s63, s23, 0
	global_load_dwordx4 v[86:89], v146, s[62:63] offset:512
	s_waitcnt vmcnt(15)
	v_pk_fma_f32 v[152:153], v[66:67], v[156:157], v[152:153]
	v_pk_fma_f32 v[154:155], v[68:69], v[158:159], v[154:155]
	s_add_u32 vcc_lo, s20, 0xb0000
	s_addc_u32 vcc_hi, s21, 0
	global_store_dwordx4 v146, v[152:155], vcc offset:64
	s_add_u32 s62, s22, 0xb0000
	s_addc_u32 s63, s23, 0
	global_load_dwordx4 v[110:113], v146, s[62:63] offset:512
	s_waitcnt vmcnt(9)
	v_pk_mul_f32 v[94:95], v[94:95], 0.5 op_sel_hi:[1,0]
	v_pk_mul_f32 v[96:97], v[96:97], 0.5 op_sel_hi:[1,0]
	s_waitcnt vmcnt(15)
	v_pk_fma_f32 v[98:99], v[62:63], v[94:95], v[98:99]
	v_pk_fma_f32 v[100:101], v[64:65], v[96:97], v[100:101]
	global_store_dwordx4 v146, v[98:101], s[20:21] offset:512
	global_load_dwordx4 v[82:85], v146, s[22:23] offset:576
	s_waitcnt vmcnt(15)
	v_pk_fma_f32 v[118:119], v[58:59], v[94:95], v[118:119]
	v_pk_fma_f32 v[120:121], v[60:61], v[96:97], v[120:121]
	s_add_u32 vcc_lo, s20, 0x10000
	s_addc_u32 vcc_hi, s21, 0
	global_store_dwordx4 v146, v[118:121], vcc offset:512
	s_add_u32 s62, s22, 0x10000
	s_addc_u32 s63, s23, 0
	global_load_dwordx4 v[142:145], v146, s[62:63] offset:576
	s_waitcnt vmcnt(15)
	v_pk_fma_f32 v[138:139], v[54:55], v[94:95], v[138:139]
	v_pk_fma_f32 v[140:141], v[56:57], v[96:97], v[140:141]
	s_add_u32 vcc_lo, s20, 0x20000
	s_addc_u32 vcc_hi, s21, 0
	global_store_dwordx4 v146, v[138:141], vcc offset:512
	s_add_u32 s62, s22, 0x20000
	s_addc_u32 s63, s23, 0
	global_load_dwordx4 v[78:81], v146, s[62:63] offset:576
	s_waitcnt vmcnt(14)
	v_pk_fma_f32 v[114:115], v[50:51], v[94:95], v[114:115]
	v_pk_fma_f32 v[116:117], v[52:53], v[96:97], v[116:117]
	s_add_u32 vcc_lo, s20, 0x30000
	s_addc_u32 vcc_hi, s21, 0
	global_store_dwordx4 v146, v[114:117], vcc offset:512
	global_load_dwordx4 v[106:109], v[160:161], off offset:576
	s_add_u32 s62, s22, 0x30000
	s_addc_u32 s63, s23, 0
	global_load_dwordx4 v[74:77], v146, s[62:63] offset:576
	s_waitcnt vmcnt(15)
	v_pk_fma_f32 v[90:91], v[46:47], v[94:95], v[90:91]
	v_pk_fma_f32 v[92:93], v[48:49], v[96:97], v[92:93]
	s_add_u32 vcc_lo, s20, 0x80000
	s_addc_u32 vcc_hi, s21, 0
	global_store_dwordx4 v146, v[90:93], vcc offset:512
	s_add_u32 s62, s22, 0x80000
	s_addc_u32 s63, s23, 0
	global_load_dwordx4 v[122:125], v146, s[62:63] offset:576
	s_waitcnt vmcnt(15)
	v_pk_fma_f32 v[126:127], v[42:43], v[94:95], v[126:127]
	v_pk_fma_f32 v[128:129], v[44:45], v[96:97], v[128:129]
	s_add_u32 vcc_lo, s20, 0x90000
	s_addc_u32 vcc_hi, s21, 0
	global_store_dwordx4 v146, v[126:129], vcc offset:512
	s_add_u32 s62, s22, 0x90000
	s_addc_u32 s63, s23, 0
	global_load_dwordx4 v[70:73], v146, s[62:63] offset:576
	s_waitcnt vmcnt(15)
	v_pk_fma_f32 v[86:87], v[38:39], v[94:95], v[86:87]
	v_pk_fma_f32 v[88:89], v[40:41], v[96:97], v[88:89]
	s_add_u32 vcc_lo, s20, 0xa0000
	s_addc_u32 vcc_hi, s21, 0
	global_store_dwordx4 v146, v[86:89], vcc offset:512
	s_add_u32 s62, s22, 0xa0000
	s_addc_u32 s63, s23, 0
	global_load_dwordx4 v[102:105], v146, s[62:63] offset:576
	s_waitcnt vmcnt(15)
	v_pk_fma_f32 v[110:111], v[34:35], v[94:95], v[110:111]
	v_pk_fma_f32 v[112:113], v[36:37], v[96:97], v[112:113]
	s_add_u32 vcc_lo, s20, 0xb0000
	s_addc_u32 vcc_hi, s21, 0
	global_store_dwordx4 v146, v[110:113], vcc offset:512
	s_add_u32 s62, s22, 0xb0000
	s_addc_u32 s63, s23, 0
	global_load_dwordx4 v[66:69], v146, s[62:63] offset:576
	s_waitcnt vmcnt(9)
	v_pk_mul_f32 v[106:107], v[106:107], 0.5 op_sel_hi:[1,0]
	v_pk_mul_f32 v[108:109], v[108:109], 0.5 op_sel_hi:[1,0]
	s_waitcnt vmcnt(15)
	v_pk_fma_f32 v[82:83], v[30:31], v[106:107], v[82:83]
	v_pk_fma_f32 v[84:85], v[32:33], v[108:109], v[84:85]
	global_store_dwordx4 v146, v[82:85], s[20:21] offset:576
	s_waitcnt vmcnt(14)
	v_pk_fma_f32 v[142:143], v[26:27], v[106:107], v[142:143]
	v_pk_fma_f32 v[144:145], v[28:29], v[108:109], v[144:145]
	s_add_u32 vcc_lo, s20, 0x10000
	s_addc_u32 vcc_hi, s21, 0
	global_store_dwordx4 v146, v[142:145], vcc offset:576
	s_waitcnt vmcnt(13)
	v_pk_fma_f32 v[78:79], v[22:23], v[106:107], v[78:79]
	v_pk_fma_f32 v[80:81], v[24:25], v[108:109], v[80:81]
	s_add_u32 vcc_lo, s20, 0x20000
	s_addc_u32 vcc_hi, s21, 0
	global_store_dwordx4 v146, v[78:81], vcc offset:576
	s_waitcnt vmcnt(11)
	v_pk_fma_f32 v[74:75], v[18:19], v[106:107], v[74:75]
	v_pk_fma_f32 v[76:77], v[20:21], v[108:109], v[76:77]
	s_add_u32 vcc_lo, s20, 0x30000
	s_addc_u32 vcc_hi, s21, 0
	global_store_dwordx4 v146, v[74:77], vcc offset:576
	s_waitcnt vmcnt(10)
	v_pk_fma_f32 v[122:123], v[14:15], v[106:107], v[122:123]
	v_pk_fma_f32 v[124:125], v[16:17], v[108:109], v[124:125]
	s_add_u32 vcc_lo, s20, 0x80000
	s_addc_u32 vcc_hi, s21, 0
	global_store_dwordx4 v146, v[122:125], vcc offset:576
	s_waitcnt vmcnt(9)
	v_pk_fma_f32 v[70:71], v[10:11], v[106:107], v[70:71]
	v_pk_fma_f32 v[72:73], v[12:13], v[108:109], v[72:73]
	s_add_u32 vcc_lo, s20, 0x90000
	s_addc_u32 vcc_hi, s21, 0
	global_store_dwordx4 v146, v[70:73], vcc offset:576
	s_waitcnt vmcnt(8)
	v_pk_fma_f32 v[102:103], v[6:7], v[106:107], v[102:103]
	v_pk_fma_f32 v[104:105], v[8:9], v[108:109], v[104:105]
	s_add_u32 vcc_lo, s20, 0xa0000
	s_addc_u32 vcc_hi, s21, 0
	global_store_dwordx4 v146, v[102:105], vcc offset:576
	s_waitcnt vmcnt(7)
	v_pk_fma_f32 v[66:67], v[2:3], v[106:107], v[66:67]
	v_pk_fma_f32 v[68:69], v[4:5], v[108:109], v[68:69]
	s_add_u32 vcc_lo, s20, 0xb0000
	s_addc_u32 vcc_hi, s21, 0
	global_store_dwordx4 v146, v[66:69], vcc offset:576
	s_mov_b32 s11, 0
	s_mov_b64 s[62:63], 0xb0000
	s_mov_b64 s[20:21], -1
	s_and_b64 vcc, exec, s[0:1]
	s_cbranch_vccnz .LBB0_351
	s_andn2_b64 vcc, exec, s[14:15]
	s_cbranch_vccnz .LBB0_350
	s_barrier
	s_branch .LBB0_350
